# speedup vs baseline: 1.0296x; 1.0089x over previous
; __device__ __forceinline__ int tid_op() { int t = threadIdx.x & 255; asm volatile("" : "+v"(t)); return t; }
; __device__ __forceinline__ int vb_op() { return (int)(blockIdx.x << 1) | sub_op(); }
; __device__ void ssd_scan_phase(const Params& p) {
;   const int nthr = p.nblk * 256;
;   for (int s = vb_op() * 256 + tid_op(); s < 131072; s += nthr) {
;     const int n2 = s & 63, pp = (s >> 6) & 63, h = (s >> 12) & 15, b = s >> 16;
;     const size_t off = (size_t)h * 8192 + pp * 128 + n2 * 2;
;     float c0 = 0.f, c1 = 0.f;
; #pragma unroll 8
;     for (int c = 0; c < 128; ++c) {
;       const size_t o = (size_t)(b * 128 + c) * 131072 + off;
;       const float2 st = *(const float2*)(p.states + o);
;       const float dec = p.cdecay[(b * 128 + c) * 16 + h];
;       *(u32*)(p.prev + o) = pack2(c0, c1);
;       c0 = c0 * dec + st.x;
;       c1 = c1 * dec + st.y;
;     }
;   }
; }
.LBB0_393:
	s_mov_b32 s96, 0xffc80000
	s_mov_b32 s97, -1
	v_lshl_add_u64 v[2:3], v[2:3], 0, s[96:97]
	s_mov_b32 s96, 0xffe40000
	v_lshl_add_u64 v[0:1], v[0:1], 0, s[96:97]
	v_ashrrev_i32_e32 v9, 31, v8
	v_lshl_add_u64 v[10:11], v[8:9], 2, s[42:43]
	s_mov_b64 s[98:99], 0x80000
	s_mov_b64 s[100:101], 0x40000
	s_mov_b64 s[96:97], 0x400
.Lscan_loop:
	v_lshl_add_u64 v[32:33], v[2:3], 0, 0
	v_lshl_add_u64 v[34:35], v[32:33], 0, s[98:99]
	v_lshl_add_u64 v[36:37], v[34:35], 0, s[98:99]
	v_lshl_add_u64 v[38:39], v[36:37], 0, s[98:99]
	v_lshl_add_u64 v[40:41], v[38:39], 0, s[98:99]
	v_lshl_add_u64 v[42:43], v[40:41], 0, s[98:99]
	v_lshl_add_u64 v[44:45], v[42:43], 0, s[98:99]
	v_lshl_add_u64 v[46:47], v[44:45], 0, s[98:99]
	v_lshl_add_u64 v[48:49], v[46:47], 0, s[98:99]
	v_lshl_add_u64 v[50:51], v[48:49], 0, s[98:99]
	v_lshl_add_u64 v[52:53], v[50:51], 0, s[98:99]
	v_lshl_add_u64 v[54:55], v[52:53], 0, s[98:99]
	v_lshl_add_u64 v[56:57], v[54:55], 0, s[98:99]
	v_lshl_add_u64 v[58:59], v[56:57], 0, s[98:99]
	v_lshl_add_u64 v[60:61], v[58:59], 0, s[98:99]
	v_lshl_add_u64 v[62:63], v[60:61], 0, s[98:99]
	global_load_dwordx2 v[64:65], v[32:33], off
	global_load_dwordx2 v[66:67], v[34:35], off
	global_load_dwordx2 v[68:69], v[36:37], off
	global_load_dwordx2 v[70:71], v[38:39], off
	global_load_dwordx2 v[72:73], v[40:41], off
	global_load_dwordx2 v[74:75], v[42:43], off
	global_load_dwordx2 v[76:77], v[44:45], off
	global_load_dwordx2 v[78:79], v[46:47], off
	global_load_dwordx2 v[80:81], v[48:49], off
	global_load_dwordx2 v[82:83], v[50:51], off
	global_load_dwordx2 v[84:85], v[52:53], off
	global_load_dwordx2 v[86:87], v[54:55], off
	global_load_dwordx2 v[88:89], v[56:57], off
	global_load_dwordx2 v[90:91], v[58:59], off
	global_load_dwordx2 v[92:93], v[60:61], off
	global_load_dwordx2 v[94:95], v[62:63], off
	global_load_dword v96, v[10:11], off
	global_load_dword v98, v[10:11], off offset:64
	global_load_dword v100, v[10:11], off offset:128
	global_load_dword v102, v[10:11], off offset:192
	global_load_dword v104, v[10:11], off offset:256
	global_load_dword v106, v[10:11], off offset:320
	global_load_dword v108, v[10:11], off offset:384
	global_load_dword v110, v[10:11], off offset:448
	global_load_dword v112, v[10:11], off offset:512
	global_load_dword v114, v[10:11], off offset:576
	global_load_dword v116, v[10:11], off offset:640
	global_load_dword v118, v[10:11], off offset:704
	global_load_dword v120, v[10:11], off offset:768
	global_load_dword v122, v[10:11], off offset:832
	global_load_dword v124, v[10:11], off offset:896
	global_load_dword v126, v[10:11], off offset:960
	v_lshl_add_u64 v[32:33], v[0:1], 0, 0
	v_lshl_add_u64 v[34:35], v[32:33], 0, s[100:101]
	v_lshl_add_u64 v[36:37], v[34:35], 0, s[100:101]
	v_lshl_add_u64 v[38:39], v[36:37], 0, s[100:101]
	v_lshl_add_u64 v[40:41], v[38:39], 0, s[100:101]
	v_lshl_add_u64 v[42:43], v[40:41], 0, s[100:101]
	v_lshl_add_u64 v[44:45], v[42:43], 0, s[100:101]
	v_lshl_add_u64 v[46:47], v[44:45], 0, s[100:101]
	v_lshl_add_u64 v[48:49], v[46:47], 0, s[100:101]
	v_lshl_add_u64 v[50:51], v[48:49], 0, s[100:101]
	v_lshl_add_u64 v[52:53], v[50:51], 0, s[100:101]
	v_lshl_add_u64 v[54:55], v[52:53], 0, s[100:101]
	v_lshl_add_u64 v[56:57], v[54:55], 0, s[100:101]
	v_lshl_add_u64 v[58:59], v[56:57], 0, s[100:101]
	v_lshl_add_u64 v[60:61], v[58:59], 0, s[100:101]
	v_lshl_add_u64 v[62:63], v[60:61], 0, s[100:101]
	s_waitcnt vmcnt(15)
	v_cvt_pk_bf16_f32 v12, v4, v5
	global_store_dword v[32:33], v12, off
	v_pk_fma_f32 v[4:5], v[4:5], v[96:97], v[64:65] op_sel_hi:[1,0,1]
	s_nop 0
	s_waitcnt vmcnt(15)
	v_cvt_pk_bf16_f32 v13, v4, v5
	global_store_dword v[34:35], v13, off
	v_pk_fma_f32 v[4:5], v[4:5], v[98:99], v[66:67] op_sel_hi:[1,0,1]
	s_nop 0
	s_waitcnt vmcnt(15)
	v_cvt_pk_bf16_f32 v12, v4, v5
	global_store_dword v[36:37], v12, off
	v_pk_fma_f32 v[4:5], v[4:5], v[100:101], v[68:69] op_sel_hi:[1,0,1]
	s_nop 0
	s_waitcnt vmcnt(15)
	v_cvt_pk_bf16_f32 v13, v4, v5
	global_store_dword v[38:39], v13, off
	v_pk_fma_f32 v[4:5], v[4:5], v[102:103], v[70:71] op_sel_hi:[1,0,1]
	s_nop 0
	s_waitcnt vmcnt(15)
	v_cvt_pk_bf16_f32 v12, v4, v5
	global_store_dword v[40:41], v12, off
	v_pk_fma_f32 v[4:5], v[4:5], v[104:105], v[72:73] op_sel_hi:[1,0,1]
	s_nop 0
	s_waitcnt vmcnt(15)
	v_cvt_pk_bf16_f32 v13, v4, v5
	global_store_dword v[42:43], v13, off
	v_pk_fma_f32 v[4:5], v[4:5], v[106:107], v[74:75] op_sel_hi:[1,0,1]
	s_nop 0
	s_waitcnt vmcnt(15)
	v_cvt_pk_bf16_f32 v12, v4, v5
	global_store_dword v[44:45], v12, off
	v_pk_fma_f32 v[4:5], v[4:5], v[108:109], v[76:77] op_sel_hi:[1,0,1]
	s_nop 0
	s_waitcnt vmcnt(15)
	v_cvt_pk_bf16_f32 v13, v4, v5
	global_store_dword v[46:47], v13, off
	v_pk_fma_f32 v[4:5], v[4:5], v[110:111], v[78:79] op_sel_hi:[1,0,1]
	s_nop 0
	s_waitcnt vmcnt(15)
	v_cvt_pk_bf16_f32 v12, v4, v5
	global_store_dword v[48:49], v12, off
	v_pk_fma_f32 v[4:5], v[4:5], v[112:113], v[80:81] op_sel_hi:[1,0,1]
	s_nop 0
	s_waitcnt vmcnt(15)
	v_cvt_pk_bf16_f32 v13, v4, v5
	global_store_dword v[50:51], v13, off
	v_pk_fma_f32 v[4:5], v[4:5], v[114:115], v[82:83] op_sel_hi:[1,0,1]
	s_nop 0
	s_waitcnt vmcnt(15)
	v_cvt_pk_bf16_f32 v12, v4, v5
	global_store_dword v[52:53], v12, off
	v_pk_fma_f32 v[4:5], v[4:5], v[116:117], v[84:85] op_sel_hi:[1,0,1]
	s_nop 0
	s_waitcnt vmcnt(15)
	v_cvt_pk_bf16_f32 v13, v4, v5
	global_store_dword v[54:55], v13, off
	v_pk_fma_f32 v[4:5], v[4:5], v[118:119], v[86:87] op_sel_hi:[1,0,1]
	s_nop 0
	s_waitcnt vmcnt(15)
	v_cvt_pk_bf16_f32 v12, v4, v5
	global_store_dword v[56:57], v12, off
	v_pk_fma_f32 v[4:5], v[4:5], v[120:121], v[88:89] op_sel_hi:[1,0,1]
	s_nop 0
	s_waitcnt vmcnt(15)
	v_cvt_pk_bf16_f32 v13, v4, v5
	global_store_dword v[58:59], v13, off
	v_pk_fma_f32 v[4:5], v[4:5], v[122:123], v[90:91] op_sel_hi:[1,0,1]
	s_nop 0
	s_waitcnt vmcnt(15)
	v_cvt_pk_bf16_f32 v12, v4, v5
	global_store_dword v[60:61], v12, off
	v_pk_fma_f32 v[4:5], v[4:5], v[124:125], v[92:93] op_sel_hi:[1,0,1]
	s_nop 0
	s_waitcnt vmcnt(15)
	v_cvt_pk_bf16_f32 v13, v4, v5
	global_store_dword v[62:63], v13, off
	v_pk_fma_f32 v[4:5], v[4:5], v[126:127], v[94:95] op_sel_hi:[1,0,1]
	s_nop 0
	v_lshl_add_u64 v[2:3], v[2:3], 0, s[10:11]
	v_lshl_add_u64 v[2:3], v[2:3], 0, s[10:11]
	v_lshl_add_u64 v[0:1], v[0:1], 0, s[10:11]
	v_lshl_add_u64 v[10:11], v[10:11], 0, s[96:97]
	s_addk_i32 s21, 0x100
	s_cmpk_eq_i32 s21, 0x800
	s_cbranch_scc0 .Lscan_loop
	v_add_u32_e32 v6, s12, v6
	v_cmp_lt_i32_e32 vcc, s20, v6
	s_or_b64 s[6:7], vcc, s[6:7]
	v_add_u32_e32 v7, s13, v7
	s_andn2_b64 exec, exec, s[6:7]
	s_cbranch_execnz .LBB0_392

; __device__ __forceinline__ int sub_op() { return __builtin_amdgcn_readfirstlane((int)(threadIdx.x >> 8)); }
; #define LAS __attribute__((address_space(3)))
; __global__ void __launch_bounds__(512, 2) mega_kernel(Params p) {
;   __shared__ __attribute__((aligned(16))) char smem[2 * SMEM_BYTES + 16];
;   __shared__ uint4 xb_words;
;   if (threadIdx.x == 0) xb_words = make_uint4(0u, 0u, 0u, 0u);
;   __syncthreads();
;   const XcdBarrier xb = xcd_barrier_post(p.bar, (volatile LAS unsigned*)&xb_words, (unsigned)(p.nblk >> 1));
;   run_range<0, NPHASE>(p, smem + sub_op() * SMEM_BYTES, smem, xb);
; }
	.amdhsa_kernel _Z11mega_kernel6Params
		.amdhsa_group_segment_fixed_size 155680
		.amdhsa_private_segment_fixed_size 0
		.amdhsa_kernarg_size 592
		.amdhsa_user_sgpr_count 2
		.amdhsa_user_sgpr_dispatch_ptr 0
		.amdhsa_user_sgpr_queue_ptr 0
		.amdhsa_user_sgpr_kernarg_segment_ptr 1
		.amdhsa_user_sgpr_dispatch_id 0
		.amdhsa_user_sgpr_kernarg_preload_length 0
		.amdhsa_user_sgpr_kernarg_preload_offset 0
		.amdhsa_user_sgpr_private_segment_size 0
		.amdhsa_uses_dynamic_stack 0
		.amdhsa_enable_private_segment 0
		.amdhsa_system_sgpr_workgroup_id_x 1
		.amdhsa_system_sgpr_workgroup_id_y 0
		.amdhsa_system_sgpr_workgroup_id_z 0
		.amdhsa_system_sgpr_workgroup_info 0
		.amdhsa_system_vgpr_workitem_id 2
		.amdhsa_next_free_vgpr 256
		.amdhsa_next_free_sgpr 102
		.amdhsa_accum_offset 256
		.amdhsa_reserve_vcc 1
		.amdhsa_float_round_mode_32 0
		.amdhsa_float_round_mode_16_64 0
		.amdhsa_float_denorm_mode_32 3
		.amdhsa_float_denorm_mode_16_64 3
		.amdhsa_dx10_clamp 1
		.amdhsa_ieee_mode 1
		.amdhsa_fp16_overflow 0
		.amdhsa_tg_split 0
		.amdhsa_exception_fp_ieee_invalid_op 0
		.amdhsa_exception_fp_denorm_src 0
		.amdhsa_exception_fp_ieee_div_zero 0
		.amdhsa_exception_fp_ieee_overflow 0
		.amdhsa_exception_fp_ieee_underflow 0
		.amdhsa_exception_fp_ieee_inexact 0
		.amdhsa_exception_int_div_zero 0
	.end_amdhsa_kernel

; __device__ __forceinline__ int sub_op() { return __builtin_amdgcn_readfirstlane((int)(threadIdx.x >> 8)); }
; #define LAS __attribute__((address_space(3)))
; __global__ void __launch_bounds__(512, 2) mega_kernel(Params p) {
;   __shared__ __attribute__((aligned(16))) char smem[2 * SMEM_BYTES + 16];
;   __shared__ uint4 xb_words;
;   if (threadIdx.x == 0) xb_words = make_uint4(0u, 0u, 0u, 0u);
;   __syncthreads();
;   const XcdBarrier xb = xcd_barrier_post(p.bar, (volatile LAS unsigned*)&xb_words, (unsigned)(p.nblk >> 1));
;   run_range<0, NPHASE>(p, smem + sub_op() * SMEM_BYTES, smem, xb);
; }
amdhsa.kernels:
  - .agpr_count:     0
    .args:
      - .offset:         0
        .size:           336
        .value_kind:     by_value
      - .offset:         336
        .size:           4
        .value_kind:     hidden_block_count_x
      - .offset:         340
        .size:           4
        .value_kind:     hidden_block_count_y
      - .offset:         344
        .size:           4
        .value_kind:     hidden_block_count_z
      - .offset:         348
        .size:           2
        .value_kind:     hidden_group_size_x
      - .offset:         350
        .size:           2
        .value_kind:     hidden_group_size_y
      - .offset:         352
        .size:           2
        .value_kind:     hidden_group_size_z
      - .offset:         354
        .size:           2
        .value_kind:     hidden_remainder_x
      - .offset:         356
        .size:           2
        .value_kind:     hidden_remainder_y
      - .offset:         358
        .size:           2
        .value_kind:     hidden_remainder_z
      - .offset:         376
        .size:           8
        .value_kind:     hidden_global_offset_x
      - .offset:         384
        .size:           8
        .value_kind:     hidden_global_offset_y
      - .offset:         392
        .size:           8
        .value_kind:     hidden_global_offset_z
      - .offset:         400
        .size:           2
        .value_kind:     hidden_grid_dims
      - .offset:         424
        .size:           8
        .value_kind:     hidden_multigrid_sync_arg
    .group_segment_fixed_size: 155680
    .kernarg_segment_align: 8
    .kernarg_segment_size: 592
    .language:       OpenCL C
    .language_version:
      - 2
      - 0
    .max_flat_workgroup_size: 512
    .name:           _Z11mega_kernel6Params
    .private_segment_fixed_size: 0
    .sgpr_count:     108
    .sgpr_spill_count: 159
    .symbol:         _Z11mega_kernel6Params.kd
    .uniform_work_group_size: 1
    .uses_dynamic_stack: false
    .vgpr_count:     256
    .vgpr_spill_count: 0
    .wavefront_size: 64
